# attention loop with fewer VALU ops per tile: score tiles accumulate onto -rowmax blocks (no per-element subtract), row max crosses wave halves with v_permlane32_swap instead of ds_bpermute, K/V stream
# speedup vs baseline: 1.0152x; 1.0141x over previous
.LBB0_346:
	s_mov_b64 s[98:99], s[88:89]
	s_mov_b64 s[100:101], s[88:89]
.Lat_loop:
	s_cmp_lg_u32 s1, 64
	s_cselect_b64 s[28:29], -1, 0
	s_and_b32 s4, 1, s1
	s_cselect_b32 s5, 0, 0x5800
	v_add3_u32 v235, s5, v223, v198
	v_add_u32_e32 v218, s5, v224
	ds_read_b128 v[236:239], v235
	ds_read_b128 v[240:243], v235 offset:6656
	ds_read_b128 v[244:247], v235 offset:32
	ds_read_b128 v[248:251], v235 offset:6688
	v_sub_f32_e32 v176, 0, v233
	v_sub_f32_e32 v177, 0, v233
	v_sub_f32_e32 v178, 0, v233
	v_sub_f32_e32 v179, 0, v233
	v_sub_f32_e32 v180, 0, v233
	v_sub_f32_e32 v181, 0, v233
	v_sub_f32_e32 v182, 0, v233
	v_sub_f32_e32 v183, 0, v233
	v_sub_f32_e32 v184, 0, v233
	v_sub_f32_e32 v185, 0, v233
	v_sub_f32_e32 v186, 0, v233
	v_sub_f32_e32 v187, 0, v233
	v_sub_f32_e32 v188, 0, v233
	v_sub_f32_e32 v189, 0, v233
	v_sub_f32_e32 v190, 0, v233
	v_sub_f32_e32 v191, 0, v233
	v_sub_f32_e32 v80, 0, v234
	v_sub_f32_e32 v81, 0, v234
	v_sub_f32_e32 v82, 0, v234
	v_sub_f32_e32 v83, 0, v234
	v_sub_f32_e32 v84, 0, v234
	v_sub_f32_e32 v85, 0, v234
	v_sub_f32_e32 v86, 0, v234
	v_sub_f32_e32 v87, 0, v234
	v_sub_f32_e32 v88, 0, v234
	v_sub_f32_e32 v89, 0, v234
	v_sub_f32_e32 v90, 0, v234
	v_sub_f32_e32 v91, 0, v234
	v_sub_f32_e32 v92, 0, v234
	v_sub_f32_e32 v93, 0, v234
	v_sub_f32_e32 v94, 0, v234
	v_sub_f32_e32 v95, 0, v234
	s_waitcnt lgkmcnt(3)
	v_mfma_f32_32x32x16_bf16 v[64:79], v[236:239], v[128:131], v[176:191]
	v_mfma_f32_32x32x16_bf16 v[96:111], v[236:239], v[152:155], v[80:95]
	ds_read_b128 v[236:239], v235 offset:64
	s_waitcnt lgkmcnt(3)
	v_mfma_f32_32x32x16_bf16 v[112:127], v[240:243], v[152:155], v[80:95]
	v_mfma_f32_32x32x16_bf16 v[80:95], v[240:243], v[128:131], v[176:191]
	ds_read_b128 v[240:243], v235 offset:6720
	s_waitcnt lgkmcnt(3)
	v_mfma_f32_32x32x16_bf16 v[64:79], v[244:247], v[132:135], v[64:79]
	v_mfma_f32_32x32x16_bf16 v[96:111], v[244:247], v[156:159], v[96:111]
	ds_read_b128 v[244:247], v235 offset:96
	s_waitcnt lgkmcnt(3)
	v_mfma_f32_32x32x16_bf16 v[80:95], v[248:251], v[132:135], v[80:95]
	v_mfma_f32_32x32x16_bf16 v[112:127], v[248:251], v[156:159], v[112:127]
	ds_read_b128 v[248:251], v235 offset:6752
	s_cmp_lg_u32 s1, 64
	s_cbranch_scc0 .Lat_skipld
	global_load_dwordx4 v[176:179], v208, s[98:99]
	global_load_dwordx4 v[180:183], v210, s[98:99]
	global_load_dwordx4 v[184:187], v212, s[98:99]
	global_load_dwordx4 v[188:191], v204, s[100:101]
	global_load_dwordx4 v[192:195], v206, s[100:101]
.Lat_skipld:
	s_waitcnt lgkmcnt(3)
	v_mfma_f32_32x32x16_bf16 v[64:79], v[236:239], v[136:139], v[64:79]
	v_mfma_f32_32x32x16_bf16 v[96:111], v[236:239], v[160:163], v[96:111]
	ds_read_b128 v[236:239], v235 offset:128
	s_waitcnt lgkmcnt(3)
	v_mfma_f32_32x32x16_bf16 v[80:95], v[240:243], v[136:139], v[80:95]
	v_mfma_f32_32x32x16_bf16 v[112:127], v[240:243], v[160:163], v[112:127]
	ds_read_b128 v[240:243], v235 offset:6784
	s_waitcnt lgkmcnt(3)
	v_mfma_f32_32x32x16_bf16 v[64:79], v[244:247], v[140:143], v[64:79]
	v_mfma_f32_32x32x16_bf16 v[96:111], v[244:247], v[164:167], v[96:111]
	ds_read_b128 v[244:247], v235 offset:160
	s_waitcnt lgkmcnt(3)
	v_mfma_f32_32x32x16_bf16 v[80:95], v[248:251], v[140:143], v[80:95]
	v_mfma_f32_32x32x16_bf16 v[112:127], v[248:251], v[164:167], v[112:127]
	ds_read_b128 v[248:251], v235 offset:6816
	s_waitcnt lgkmcnt(3)
	v_mfma_f32_32x32x16_bf16 v[64:79], v[236:239], v[144:147], v[64:79]
	v_mfma_f32_32x32x16_bf16 v[96:111], v[236:239], v[168:171], v[96:111]
	ds_read_b128 v[236:239], v218 offset:13312
	s_waitcnt lgkmcnt(3)
	v_mfma_f32_32x32x16_bf16 v[80:95], v[240:243], v[144:147], v[80:95]
	v_mfma_f32_32x32x16_bf16 v[112:127], v[240:243], v[168:171], v[112:127]
	ds_read_b128 v[240:243], v218 offset:17920
	s_waitcnt lgkmcnt(3)
	v_mfma_f32_32x32x16_bf16 v[64:79], v[244:247], v[148:151], v[64:79]
	v_mfma_f32_32x32x16_bf16 v[96:111], v[244:247], v[172:175], v[96:111]
	s_waitcnt lgkmcnt(2)
	v_mfma_f32_32x32x16_bf16 v[80:95], v[248:251], v[148:151], v[80:95]
	v_mfma_f32_32x32x16_bf16 v[112:127], v[248:251], v[172:175], v[112:127]
	ds_read_b128 v[244:247], v218 offset:13344
	ds_read_b128 v[248:251], v218 offset:17952
	s_nop 7
	s_nop 1
	v_max3_f32 v214, v64, v65, v66
	v_max3_f32 v215, v80, v81, v82
	v_max3_f32 v216, v96, v97, v98
	v_max3_f32 v217, v112, v113, v114
	v_max3_f32 v214, v214, v67, v68
	v_max3_f32 v215, v215, v83, v84
	v_max3_f32 v216, v216, v99, v100
	v_max3_f32 v217, v217, v115, v116
	v_max3_f32 v214, v214, v69, v70
	v_max3_f32 v215, v215, v85, v86
	v_max3_f32 v216, v216, v101, v102
	v_max3_f32 v217, v217, v117, v118
	v_max3_f32 v214, v214, v71, v72
	v_max3_f32 v215, v215, v87, v88
	v_max3_f32 v216, v216, v103, v104
	v_max3_f32 v217, v217, v119, v120
	v_max3_f32 v214, v214, v73, v74
	v_max3_f32 v215, v215, v89, v90
	v_max3_f32 v216, v216, v105, v106
	v_max3_f32 v217, v217, v121, v122
	v_max3_f32 v214, v214, v75, v76
	v_max3_f32 v215, v215, v91, v92
	v_max3_f32 v216, v216, v107, v108
	v_max3_f32 v217, v217, v123, v124
	v_max3_f32 v214, v214, v77, v78
	v_max3_f32 v215, v215, v93, v94
	v_max3_f32 v216, v216, v109, v110
	v_max3_f32 v217, v217, v125, v126
	v_max_f32_e32 v214, v214, v79
	v_max_f32_e32 v215, v215, v95
	v_max_f32_e32 v216, v216, v111
	v_max_f32_e32 v217, v217, v127
	v_max_f32_e32 v214, v214, v215
	v_max_f32_e32 v216, v216, v217
	v_mov_b32_e32 v215, v214
	v_mov_b32_e32 v217, v216
	s_nop 1
	v_permlane32_swap_b32 v214, v215
	v_permlane32_swap_b32 v216, v217
	v_max_f32_e32 v214, v214, v215
	v_max_f32_e32 v216, v216, v217
	v_cmp_lt_f32_e32 vcc, s56, v214
	s_cbranch_vccz .Lat_nr0
	v_max_f32_e32 v215, 0, v214
	v_sub_f32_e32 v196, 0, v215
	v_exp_f32_e32 v196, v196
	v_add_f32_e32 v233, v233, v215
	s_nop 0
	v_mul_f32_e32 v202, v196, v202
	v_mul_f32_e32 v0, v196, v0
	v_mul_f32_e32 v1, v196, v1
	v_mul_f32_e32 v2, v196, v2
	v_mul_f32_e32 v3, v196, v3
	v_mul_f32_e32 v4, v196, v4
	v_mul_f32_e32 v5, v196, v5
	v_mul_f32_e32 v6, v196, v6
	v_mul_f32_e32 v7, v196, v7
	v_mul_f32_e32 v8, v196, v8
	v_mul_f32_e32 v9, v196, v9
	v_mul_f32_e32 v10, v196, v10
	v_mul_f32_e32 v11, v196, v11
	v_mul_f32_e32 v12, v196, v12
	v_mul_f32_e32 v13, v196, v13
	v_mul_f32_e32 v14, v196, v14
	v_mul_f32_e32 v15, v196, v15
	v_mul_f32_e32 v16, v196, v16
	v_mul_f32_e32 v17, v196, v17
	v_mul_f32_e32 v18, v196, v18
	v_mul_f32_e32 v19, v196, v19
	v_mul_f32_e32 v20, v196, v20
	v_mul_f32_e32 v21, v196, v21
	v_mul_f32_e32 v22, v196, v22
	v_mul_f32_e32 v23, v196, v23
	v_mul_f32_e32 v24, v196, v24
	v_mul_f32_e32 v25, v196, v25
	v_mul_f32_e32 v26, v196, v26
	v_mul_f32_e32 v27, v196, v27
	v_mul_f32_e32 v28, v196, v28
	v_mul_f32_e32 v29, v196, v29
	v_mul_f32_e32 v30, v196, v30
	v_mul_f32_e32 v31, v196, v31
	v_sub_f32_e32 v64, v64, v215
	v_sub_f32_e32 v65, v65, v215
	v_sub_f32_e32 v66, v66, v215
	v_sub_f32_e32 v67, v67, v215
	v_sub_f32_e32 v68, v68, v215
	v_sub_f32_e32 v69, v69, v215
	v_sub_f32_e32 v70, v70, v215
	v_sub_f32_e32 v71, v71, v215
	v_sub_f32_e32 v72, v72, v215
	v_sub_f32_e32 v73, v73, v215
	v_sub_f32_e32 v74, v74, v215
	v_sub_f32_e32 v75, v75, v215
	v_sub_f32_e32 v76, v76, v215
	v_sub_f32_e32 v77, v77, v215
	v_sub_f32_e32 v78, v78, v215
	v_sub_f32_e32 v79, v79, v215
	v_sub_f32_e32 v80, v80, v215
	v_sub_f32_e32 v81, v81, v215
	v_sub_f32_e32 v82, v82, v215
	v_sub_f32_e32 v83, v83, v215
	v_sub_f32_e32 v84, v84, v215
	v_sub_f32_e32 v85, v85, v215
	v_sub_f32_e32 v86, v86, v215
	v_sub_f32_e32 v87, v87, v215
	v_sub_f32_e32 v88, v88, v215
	v_sub_f32_e32 v89, v89, v215
	v_sub_f32_e32 v90, v90, v215
	v_sub_f32_e32 v91, v91, v215
	v_sub_f32_e32 v92, v92, v215
	v_sub_f32_e32 v93, v93, v215
	v_sub_f32_e32 v94, v94, v215
	v_sub_f32_e32 v95, v95, v215

.Lat_nr1:
	v_exp_f32_e32 v64, v64
	v_exp_f32_e32 v65, v65
	v_exp_f32_e32 v66, v66
	v_exp_f32_e32 v67, v67
	v_add_f32_e32 v202, v202, v64
	v_exp_f32_e32 v68, v68
	v_exp_f32_e32 v69, v69
	v_add_f32_e32 v202, v202, v66
	v_exp_f32_e32 v70, v70
	v_add_f32_e32 v214, v65, v67
	v_cvt_pk_bf16_f32 v64, v64, v65
	v_exp_f32_e32 v71, v71
	v_add_f32_e32 v202, v202, v68
	v_exp_f32_e32 v72, v72
	v_add_f32_e32 v214, v214, v69
	v_cvt_pk_bf16_f32 v65, v66, v67
	v_exp_f32_e32 v73, v73
	v_add_f32_e32 v202, v202, v70
	v_exp_f32_e32 v74, v74
	v_add_f32_e32 v214, v214, v71
	v_cvt_pk_bf16_f32 v66, v68, v69
	v_exp_f32_e32 v75, v75
	v_add_f32_e32 v202, v202, v72
	v_exp_f32_e32 v76, v76
	v_add_f32_e32 v214, v214, v73
	v_cvt_pk_bf16_f32 v67, v70, v71
	v_exp_f32_e32 v77, v77
	v_add_f32_e32 v202, v202, v74
	s_waitcnt lgkmcnt(3)
	v_mfma_f32_32x32x16_bf16 v[16:31], v[236:239], v[64:67], v[16:31]
	v_exp_f32_e32 v78, v78
	v_add_f32_e32 v214, v214, v75
	v_cvt_pk_bf16_f32 v68, v72, v73
	v_exp_f32_e32 v79, v79
	v_add_f32_e32 v202, v202, v76
	v_exp_f32_e32 v80, v80
	v_add_f32_e32 v214, v214, v77
	v_cvt_pk_bf16_f32 v69, v74, v75
	s_waitcnt lgkmcnt(2)
	v_mfma_f32_32x32x16_bf16 v[0:15], v[240:243], v[64:67], v[0:15]
	v_exp_f32_e32 v81, v81
	v_add_f32_e32 v202, v202, v78
	v_exp_f32_e32 v82, v82
	v_add_f32_e32 v214, v214, v79
	v_cvt_pk_bf16_f32 v70, v76, v77
	v_exp_f32_e32 v83, v83
	v_add_f32_e32 v202, v202, v80
	v_exp_f32_e32 v84, v84
	v_add_f32_e32 v214, v214, v81
	v_cvt_pk_bf16_f32 v71, v78, v79
	v_exp_f32_e32 v85, v85
	v_add_f32_e32 v202, v202, v82
	s_waitcnt lgkmcnt(1)
	v_mfma_f32_32x32x16_bf16 v[16:31], v[244:247], v[68:71], v[16:31]
	v_exp_f32_e32 v86, v86
	v_add_f32_e32 v214, v214, v83
	v_cvt_pk_bf16_f32 v72, v80, v81
	v_exp_f32_e32 v87, v87
	v_add_f32_e32 v202, v202, v84
	v_exp_f32_e32 v88, v88
	v_add_f32_e32 v214, v214, v85
	v_cvt_pk_bf16_f32 v73, v82, v83
	s_waitcnt lgkmcnt(0)
	v_mfma_f32_32x32x16_bf16 v[0:15], v[248:251], v[68:71], v[0:15]
	v_exp_f32_e32 v89, v89
	v_add_f32_e32 v202, v202, v86
	v_exp_f32_e32 v90, v90
	v_add_f32_e32 v214, v214, v87
	v_cvt_pk_bf16_f32 v74, v84, v85
	v_exp_f32_e32 v91, v91
	v_add_f32_e32 v202, v202, v88
	v_exp_f32_e32 v92, v92
	v_add_f32_e32 v214, v214, v89
	v_cvt_pk_bf16_f32 v75, v86, v87
	v_exp_f32_e32 v93, v93
	v_add_f32_e32 v202, v202, v90
	v_exp_f32_e32 v94, v94
	v_add_f32_e32 v214, v214, v91
	v_cvt_pk_bf16_f32 v76, v88, v89
	v_exp_f32_e32 v95, v95
	v_add_f32_e32 v202, v202, v92
	v_add_f32_e32 v214, v214, v93
	v_cvt_pk_bf16_f32 v77, v90, v91
	v_add_f32_e32 v202, v202, v94
	v_add_f32_e32 v214, v214, v95
	v_cvt_pk_bf16_f32 v78, v92, v93
	v_cvt_pk_bf16_f32 v79, v94, v95
	v_add_f32_e32 v202, v202, v214
	ds_read_b128 v[80:83], v218 offset:13376
	ds_read_b128 v[84:87], v218 offset:17984
	ds_read_b128 v[88:91], v218 offset:13408
	ds_read_b128 v[92:95], v218 offset:18016
	v_exp_f32_e32 v96, v96
	v_exp_f32_e32 v97, v97
	v_exp_f32_e32 v98, v98
	v_exp_f32_e32 v99, v99
	v_add_f32_e32 v203, v203, v96
	v_exp_f32_e32 v100, v100
	v_exp_f32_e32 v101, v101
	v_add_f32_e32 v203, v203, v98
	v_exp_f32_e32 v102, v102
	v_add_f32_e32 v216, v97, v99
	v_cvt_pk_bf16_f32 v96, v96, v97
	v_exp_f32_e32 v103, v103
	v_add_f32_e32 v203, v203, v100
	v_exp_f32_e32 v104, v104
	s_waitcnt lgkmcnt(3)
	v_mfma_f32_32x32x16_bf16 v[16:31], v[80:83], v[72:75], v[16:31]
	v_add_f32_e32 v216, v216, v101
	v_cvt_pk_bf16_f32 v97, v98, v99
	v_exp_f32_e32 v105, v105
	v_add_f32_e32 v203, v203, v102
	v_exp_f32_e32 v106, v106
	v_add_f32_e32 v216, v216, v103
	v_cvt_pk_bf16_f32 v98, v100, v101
	v_exp_f32_e32 v107, v107
	s_waitcnt lgkmcnt(2)
	v_mfma_f32_32x32x16_bf16 v[0:15], v[84:87], v[72:75], v[0:15]
	v_add_f32_e32 v203, v203, v104
	v_exp_f32_e32 v108, v108
	v_add_f32_e32 v216, v216, v105
	v_cvt_pk_bf16_f32 v99, v102, v103
	v_exp_f32_e32 v109, v109
	v_add_f32_e32 v203, v203, v106
	v_exp_f32_e32 v110, v110
	v_add_f32_e32 v216, v216, v107
	s_waitcnt lgkmcnt(1)
	v_mfma_f32_32x32x16_bf16 v[16:31], v[88:91], v[76:79], v[16:31]
	v_cvt_pk_bf16_f32 v100, v104, v105
	v_exp_f32_e32 v111, v111
	v_add_f32_e32 v203, v203, v108
	v_exp_f32_e32 v112, v112
	v_add_f32_e32 v216, v216, v109
	v_cvt_pk_bf16_f32 v101, v106, v107
	v_exp_f32_e32 v113, v113
	v_add_f32_e32 v203, v203, v110
	s_waitcnt lgkmcnt(0)
	v_mfma_f32_32x32x16_bf16 v[0:15], v[92:95], v[76:79], v[0:15]
	v_exp_f32_e32 v114, v114
	v_add_f32_e32 v216, v216, v111
	v_cvt_pk_bf16_f32 v102, v108, v109
	v_exp_f32_e32 v115, v115
	v_add_f32_e32 v203, v203, v112
	v_exp_f32_e32 v116, v116
	v_add_f32_e32 v216, v216, v113
	v_cvt_pk_bf16_f32 v103, v110, v111
	v_mfma_f32_32x32x16_bf16 v[48:63], v[236:239], v[96:99], v[48:63]
	v_exp_f32_e32 v117, v117
	v_add_f32_e32 v203, v203, v114
	v_exp_f32_e32 v118, v118
	v_add_f32_e32 v216, v216, v115
	v_cvt_pk_bf16_f32 v104, v112, v113
	v_exp_f32_e32 v119, v119
	v_add_f32_e32 v203, v203, v116
	v_exp_f32_e32 v120, v120
	v_mfma_f32_32x32x16_bf16 v[32:47], v[240:243], v[96:99], v[32:47]
	v_add_f32_e32 v216, v216, v117
	v_cvt_pk_bf16_f32 v105, v114, v115
	v_exp_f32_e32 v121, v121
	v_add_f32_e32 v203, v203, v118
	v_exp_f32_e32 v122, v122
	v_add_f32_e32 v216, v216, v119
	v_cvt_pk_bf16_f32 v106, v116, v117
	v_exp_f32_e32 v123, v123
	v_mfma_f32_32x32x16_bf16 v[48:63], v[244:247], v[100:103], v[48:63]
	v_add_f32_e32 v203, v203, v120
	v_exp_f32_e32 v124, v124
	v_add_f32_e32 v216, v216, v121
	v_cvt_pk_bf16_f32 v107, v118, v119
	v_exp_f32_e32 v125, v125
	v_add_f32_e32 v203, v203, v122
	v_exp_f32_e32 v126, v126
	v_add_f32_e32 v216, v216, v123
	v_mfma_f32_32x32x16_bf16 v[32:47], v[248:251], v[100:103], v[32:47]
	v_cvt_pk_bf16_f32 v108, v120, v121
	v_exp_f32_e32 v127, v127
	v_add_f32_e32 v203, v203, v124
	v_add_f32_e32 v216, v216, v125
	v_cvt_pk_bf16_f32 v109, v122, v123
	v_add_f32_e32 v203, v203, v126
	v_add_f32_e32 v216, v216, v127
	v_cvt_pk_bf16_f32 v110, v124, v125
	v_cvt_pk_bf16_f32 v111, v126, v127
	v_add_f32_e32 v203, v203, v216
	s_nop 0
	v_mfma_f32_32x32x16_bf16 v[48:63], v[80:83], v[104:107], v[48:63]
	v_mfma_f32_32x32x16_bf16 v[32:47], v[84:87], v[104:107], v[32:47]
	s_cmp_eq_u32 s1, 64
	s_cbranch_scc1 .Lat_nowr
	s_cmp_eq_u32 s4, 1
	s_cselect_b32 s4, 0x5800, 0
	v_add3_u32 v214, s4, v225, v226
	v_add3_u32 v215, s4, v227, v228
	v_add3_u32 v216, s4, v229, v230
	v_add3_u32 v217, s4, v231, v200
	v_add3_u32 v196, s4, v232, v200
	s_waitcnt vmcnt(4)
	ds_write_b128 v214, v[176:179]
	s_waitcnt vmcnt(3)
	ds_write_b128 v215, v[180:183]
	s_waitcnt vmcnt(2)
	ds_write_b128 v216, v[184:187]
	s_waitcnt vmcnt(1)
	ds_write_b128 v217, v[188:191] offset:13312
	s_waitcnt vmcnt(0)
	ds_write_b128 v196, v[192:195] offset:13312
.Lat_nowr:
	v_mfma_f32_32x32x16_bf16 v[48:63], v[88:91], v[108:111], v[48:63]
	v_mfma_f32_32x32x16_bf16 v[32:47], v[92:95], v[108:111], v[32:47]
	s_add_i32 s1, s1, 1
	s_add_u32 s98, s98, s54
	s_addc_u32 s99, s99, s55
	s_add_u32 s100, s100, s76
	s_addc_u32 s101, s101, s77
	s_cmpk_eq_i32 s1, 0x41
	s_waitcnt lgkmcnt(0)
	s_barrier
	s_cbranch_scc0 .Lat_loop
	s_nop 7
	s_nop 7
	s_branch .LBB0_343
	.p2align 6
	s_nop 0
	s_nop 0
	s_nop 0
	s_nop 0
